# v59 + P3a EpiGate rewritten by hand: all 16 G loads of the unit issued up-front above the half barrier, counted vmcnt(14), saddr addressing
# speedup vs baseline: 1.0145x; 1.0061x over previous
; #define PG8_STAGE(bufoff, gbase, voff) do { _Pragma("unroll") for (int _i = 0; _i < 2; ++_i) \
;         __builtin_amdgcn_global_load_lds((const unsigned*)((const char*)(gbase) + (voff)[_i]), (PG8_LAS unsigned*)(lds + (bufoff) + ldsw + _i * 8192), 16, 0, 0); } while (0)
; #define PG8_LDA(dst, b, h) do { _Pragma("unroll") for (int m = 0; m < 4; ++m) _Pragma("unroll") for (int k = 0; k < 2; ++k) dst[m][k] = *(const PG8_LAS bf16x8*)(lds + PG8_SA(b, h) + aoff + m * 2048 + k * 1024); } while (0)
; #define PG8_LDB(dst, b, h) do { _Pragma("unroll") for (int n = 0; n < 2; ++n) _Pragma("unroll") for (int k = 0; k < 2; ++k) dst[n][k] = *(const PG8_LAS bf16x8*)(lds + PG8_SB(b, h) + boff + n * 2048 + k * 1024); } while (0)
; #define PG8_MMA(ai, bj, At, Bt) do { __builtin_amdgcn_s_setprio(1); _Pragma("unroll") for (int m = 0; m < 4; ++m) _Pragma("unroll") for (int n = 0; n < 2; ++n) _Pragma("unroll") for (int k = 0; k < 2; ++k) \
;         acc[ai][bj][m][n] = __builtin_amdgcn_mfma_f32_16x16x32_bf16(Bt[n][k], At[m][k], acc[ai][bj][m][n], 0, 0, 0); __builtin_amdgcn_s_setprio(0); } while (0)
; #define PG8_WAIT_V(n) asm volatile("s_waitcnt vmcnt(" #n ")" ::: "memory")
; #define PG8_WAIT_L(n) asm volatile("s_waitcnt lgkmcnt(" #n ")" ::: "memory")
; #define PG8_BAR __builtin_amdgcn_s_barrier()
; #define PG8_SCHED __builtin_amdgcn_sched_barrier(0)
; template <class Epi, class Sched, bool ALIGN_EPI = false, bool SP2 = false>
; __device__ __forceinline__ void gemm_phase(PG8_LAS unsigned char* lds, const Gemm g, const Sched& S, const Epi& E) {
;     ...
;             PG8_WAIT_V(8); PG8_WAIT_L(0); PG8_BAR; PG8_MMA(0, 0, At, B0); PG8_MMA(0, 1, At, B1); PG8_BAR; PG8_SCHED;
;             PG8_LDA(At, 0, 1); PG8_STAGE(PG8_SB(0, 0), b2, voffB); PG8_STAGE(PG8_SB(0, 1), b2 + hstep, voffB); PG8_STAGE(PG8_SA(0, 0), a2, voffA);
;             PG8_WAIT_V(8); PG8_WAIT_L(0); PG8_BAR; PG8_MMA(1, 0, At, B0); PG8_MMA(1, 1, At, B1); PG8_BAR; PG8_SCHED;
;             PG8_LDB(B0, 1, 0); PG8_LDB(B1, 1, 1); PG8_SCHED; PG8_LDA(At, 1, 0); PG8_STAGE(PG8_SA(0, 1), a2 + hstep, voffA);
;             PG8_WAIT_V(8); PG8_WAIT_L(0); PG8_BAR; PG8_MMA(0, 0, At, B0); PG8_MMA(0, 1, At, B1); PG8_BAR; PG8_SCHED;
.Lrj_P3a_1:
	s_waitcnt lgkmcnt(0)
	s_barrier
	s_setprio 1
	s_waitcnt lgkmcnt(0)
	v_mfma_f32_16x16x32_bf16 v[60:63], v[144:147], v[184:187], v[60:63]
	v_mfma_f32_16x16x32_bf16 v[56:59], v[160:163], v[184:187], v[56:59]
	v_mfma_f32_16x16x32_bf16 v[48:51], v[144:147], v[192:195], v[48:51]
	v_mfma_f32_16x16x32_bf16 v[40:43], v[160:163], v[192:195], v[40:43]
	v_mfma_f32_16x16x32_bf16 v[32:35], v[144:147], v[200:203], v[32:35]
	v_mfma_f32_16x16x32_bf16 v[24:27], v[160:163], v[200:203], v[24:27]
	v_mfma_f32_16x16x32_bf16 v[16:19], v[144:147], v[208:211], v[16:19]
	v_mfma_f32_16x16x32_bf16 v[8:11], v[160:163], v[208:211], v[8:11]
	v_mfma_f32_16x16x32_bf16 v[60:63], v[156:159], v[188:191], v[60:63]
	v_mfma_f32_16x16x32_bf16 v[56:59], v[164:167], v[188:191], v[56:59]
	v_mfma_f32_16x16x32_bf16 v[48:51], v[156:159], v[196:199], v[48:51]
	v_mfma_f32_16x16x32_bf16 v[40:43], v[164:167], v[196:199], v[40:43]
	v_mfma_f32_16x16x32_bf16 v[32:35], v[156:159], v[204:207], v[32:35]
	v_mfma_f32_16x16x32_bf16 v[24:27], v[164:167], v[204:207], v[24:27]
	v_mfma_f32_16x16x32_bf16 v[16:19], v[156:159], v[212:215], v[16:19]
	v_mfma_f32_16x16x32_bf16 v[8:11], v[164:167], v[212:215], v[8:11]
	s_setprio 0
	s_setprio 1
	v_mfma_f32_16x16x32_bf16 v[52:55], v[168:171], v[184:187], v[52:55]
	v_mfma_f32_16x16x32_bf16 v[44:47], v[176:179], v[184:187], v[44:47]
	v_mfma_f32_16x16x32_bf16 v[36:39], v[168:171], v[192:195], v[36:39]
	v_mfma_f32_16x16x32_bf16 v[28:31], v[176:179], v[192:195], v[28:31]
	v_mfma_f32_16x16x32_bf16 v[20:23], v[168:171], v[200:203], v[20:23]
	v_mfma_f32_16x16x32_bf16 v[12:15], v[176:179], v[200:203], v[12:15]
	v_mfma_f32_16x16x32_bf16 v[4:7], v[168:171], v[208:211], v[4:7]
	v_mfma_f32_16x16x32_bf16 v[0:3], v[176:179], v[208:211], v[0:3]
	v_mfma_f32_16x16x32_bf16 v[52:55], v[172:175], v[188:191], v[52:55]
	v_mfma_f32_16x16x32_bf16 v[44:47], v[180:183], v[188:191], v[44:47]
	v_mfma_f32_16x16x32_bf16 v[36:39], v[172:175], v[196:199], v[36:39]
	v_mfma_f32_16x16x32_bf16 v[28:31], v[180:183], v[196:199], v[28:31]
	v_mfma_f32_16x16x32_bf16 v[20:23], v[172:175], v[204:207], v[20:23]
	v_mfma_f32_16x16x32_bf16 v[12:15], v[180:183], v[204:207], v[12:15]
	v_mfma_f32_16x16x32_bf16 v[4:7], v[172:175], v[212:215], v[4:7]
	v_mfma_f32_16x16x32_bf16 v[0:3], v[180:183], v[212:215], v[0:3]
	s_setprio 0
	s_barrier
	s_add_i32 s75, 0, 0x18000
	s_add_i32 s76, 0, 0x1c000
	v_add_u32_e32 v164, s75, v151
	v_add_u32_e32 v180, s76, v151
	ds_read_b128 v[144:147], v164
	ds_read_b128 v[156:159], v164 offset:1024
	ds_read_b128 v[160:163], v164 offset:2048
	ds_read_b128 v[164:167], v164 offset:3072
	ds_read_b128 v[168:171], v180
	ds_read_b128 v[172:175], v180 offset:1024
	ds_read_b128 v[176:179], v180 offset:2048
	ds_read_b128 v[180:183], v180 offset:3072
	s_add_u32 s40, s40, 0x20000
	s_addc_u32 s41, s41, 0
	s_mov_b32 m0, s53
	v_lshl_add_u64 v[222:223], s[40:41], 0, v[134:135]
	ds_read_b128 v[184:187], v155 offset:32768
	ds_read_b128 v[188:191], v155 offset:33792
	ds_read_b128 v[192:195], v155 offset:34816
	ds_read_b128 v[196:199], v155 offset:35840
	ds_read_b128 v[200:203], v155 offset:36864
	ds_read_b128 v[204:207], v155 offset:37888
	ds_read_b128 v[208:211], v155 offset:38912
	ds_read_b128 v[212:215], v155 offset:39936
	global_load_lds_dwordx4 v[222:223], off
	v_lshl_add_u64 v[222:223], s[40:41], 0, v[130:131]
	s_mov_b32 m0, s60
	s_nop 0
	global_load_lds_dwordx4 v[222:223], off
	s_waitcnt vmcnt(8)
	s_waitcnt lgkmcnt(0)
	s_barrier
	s_setprio 1
	s_waitcnt lgkmcnt(0)
	v_mfma_f32_16x16x32_bf16 v[124:127], v[144:147], v[184:187], v[124:127]
	v_mfma_f32_16x16x32_bf16 v[120:123], v[160:163], v[184:187], v[120:123]
	v_mfma_f32_16x16x32_bf16 v[112:115], v[144:147], v[192:195], v[112:115]
	v_mfma_f32_16x16x32_bf16 v[104:107], v[160:163], v[192:195], v[104:107]
	v_mfma_f32_16x16x32_bf16 v[96:99], v[144:147], v[200:203], v[96:99]
	v_mfma_f32_16x16x32_bf16 v[88:91], v[160:163], v[200:203], v[88:91]
	v_mfma_f32_16x16x32_bf16 v[80:83], v[144:147], v[208:211], v[80:83]
	v_mfma_f32_16x16x32_bf16 v[72:75], v[160:163], v[208:211], v[72:75]
	v_mfma_f32_16x16x32_bf16 v[124:127], v[156:159], v[188:191], v[124:127]
	v_mfma_f32_16x16x32_bf16 v[120:123], v[164:167], v[188:191], v[120:123]
	v_mfma_f32_16x16x32_bf16 v[112:115], v[156:159], v[196:199], v[112:115]
	v_mfma_f32_16x16x32_bf16 v[104:107], v[164:167], v[196:199], v[104:107]
	v_mfma_f32_16x16x32_bf16 v[96:99], v[156:159], v[204:207], v[96:99]
	v_mfma_f32_16x16x32_bf16 v[88:91], v[164:167], v[204:207], v[88:91]
	v_mfma_f32_16x16x32_bf16 v[80:83], v[156:159], v[212:215], v[80:83]
	v_mfma_f32_16x16x32_bf16 v[72:75], v[164:167], v[212:215], v[72:75]
	s_setprio 0
	s_setprio 1
	v_mfma_f32_16x16x32_bf16 v[116:119], v[168:171], v[184:187], v[116:119]
	v_mfma_f32_16x16x32_bf16 v[108:111], v[176:179], v[184:187], v[108:111]
	v_mfma_f32_16x16x32_bf16 v[100:103], v[168:171], v[192:195], v[100:103]
	v_mfma_f32_16x16x32_bf16 v[92:95], v[176:179], v[192:195], v[92:95]
	v_mfma_f32_16x16x32_bf16 v[84:87], v[168:171], v[200:203], v[84:87]
	v_mfma_f32_16x16x32_bf16 v[76:79], v[176:179], v[200:203], v[76:79]
	v_mfma_f32_16x16x32_bf16 v[68:71], v[168:171], v[208:211], v[68:71]
	v_mfma_f32_16x16x32_bf16 v[64:67], v[176:179], v[208:211], v[64:67]
	v_mfma_f32_16x16x32_bf16 v[116:119], v[172:175], v[188:191], v[116:119]
	v_mfma_f32_16x16x32_bf16 v[108:111], v[180:183], v[188:191], v[108:111]
	v_mfma_f32_16x16x32_bf16 v[100:103], v[172:175], v[196:199], v[100:103]
	v_mfma_f32_16x16x32_bf16 v[92:95], v[180:183], v[196:199], v[92:95]
	v_mfma_f32_16x16x32_bf16 v[84:87], v[172:175], v[204:207], v[84:87]
	v_mfma_f32_16x16x32_bf16 v[76:79], v[180:183], v[204:207], v[76:79]
	v_mfma_f32_16x16x32_bf16 v[68:71], v[172:175], v[212:215], v[68:71]
	v_mfma_f32_16x16x32_bf16 v[64:67], v[180:183], v[212:215], v[64:67]
	s_setprio 0
	s_barrier
; #define PG8_STAGE(bufoff, gbase, voff) do { _Pragma("unroll") for (int _i = 0; _i < 2; ++_i) \
;         __builtin_amdgcn_global_load_lds((const unsigned*)((const char*)(gbase) + (voff)[_i]), (PG8_LAS unsigned*)(lds + (bufoff) + ldsw + _i * 8192), 16, 0, 0); } while (0)
; #define PG8_LDA(dst, b, h) do { _Pragma("unroll") for (int m = 0; m < 4; ++m) _Pragma("unroll") for (int k = 0; k < 2; ++k) dst[m][k] = *(const PG8_LAS bf16x8*)(lds + PG8_SA(b, h) + aoff + m * 2048 + k * 1024); } while (0)
; #define PG8_MMA(ai, bj, At, Bt) do { __builtin_amdgcn_s_setprio(1); _Pragma("unroll") for (int m = 0; m < 4; ++m) _Pragma("unroll") for (int n = 0; n < 2; ++n) _Pragma("unroll") for (int k = 0; k < 2; ++k) \
;         acc[ai][bj][m][n] = __builtin_amdgcn_mfma_f32_16x16x32_bf16(Bt[n][k], At[m][k], acc[ai][bj][m][n], 0, 0, 0); __builtin_amdgcn_s_setprio(0); } while (0)
; #define PG8_WAIT_V(n) asm volatile("s_waitcnt vmcnt(" #n ")" ::: "memory")
; #define PG8_WAIT_L(n) asm volatile("s_waitcnt lgkmcnt(" #n ")" ::: "memory")
; #define PG8_BAR __builtin_amdgcn_s_barrier()
; #define PG8_SCHED __builtin_amdgcn_sched_barrier(0)
; __device__ __forceinline__ void unpack8(const u32x4 w, f32x4& a, f32x4& b) { a = (f32x4){bflo(w.x), bfhi(w.x), bflo(w.y), bfhi(w.y)}; b = (f32x4){bflo(w.z), bfhi(w.z), bflo(w.w), bfhi(w.w)}; }
; template <class Epi, class Sched, bool ALIGN_EPI = false, bool SP2 = false>
; __device__ __forceinline__ void gemm_phase(PG8_LAS unsigned char* lds, const Gemm g, const Sched& S, const Epi& E) {
;     ...
;         for (int t = 0; t < nt; t += 2) {
;     ...
;             PG8_LDA(At, 1, 1); PG8_STAGE(PG8_SB(1, 0), b3, voffB); PG8_STAGE(PG8_SB(1, 1), b3 + hstep, voffB); PG8_STAGE(PG8_SA(1, 0), a3, voffA);
;             PG8_WAIT_V(8); PG8_WAIT_L(0); PG8_BAR; PG8_MMA(1, 0, At, B0); PG8_MMA(1, 1, At, B1); PG8_BAR; PG8_SCHED;
;     __device__ __forceinline__ void operator()(const f32x4 (&acc)[2][2][4][2], const Unit& u, int wr, int wc, int fr, int fq) const {
;         const int rbase = u.pm * 256 + wr * 64 + fr, cb = u.pn * 256 + wc * 32 + fq * 8;
; #pragma unroll
;         for (int ai = 0; ai < 2; ++ai)
; #pragma unroll
;             for (int m = 0; m < 4; ++m) { const size_t ro = (size_t)(rbase + ai * 128 + m * 16) * 1024 + cb;
; #pragma unroll
;                 for (int bj = 0; bj < 2; ++bj) { f32x4 g0, g1; unpack8(*(const u32x4*)(G + ro + bj * 128), g0, g1);
	s_add_i32 s40, s75, s43
	v_lshl_add_u64 v[148:149], v[148:149], 0, s[12:13]
	s_mov_b32 m0, s40
	ds_read_b128 v[184:187], v155 offset:49152
	ds_read_b128 v[188:191], v155 offset:50176
	ds_read_b128 v[192:195], v155 offset:51200
	ds_read_b128 v[196:199], v155 offset:52224
	ds_read_b128 v[200:203], v155 offset:53248
	ds_read_b128 v[204:207], v155 offset:54272
	ds_read_b128 v[208:211], v155 offset:55296
	ds_read_b128 v[212:215], v155 offset:56320
	global_load_lds_dwordx4 v[148:149], off
	s_add_i32 m0, s40, 0x2000
	s_add_u32 s38, s38, 0x20080
	v_lshl_add_u64 v[148:149], v[216:217], 0, s[12:13]
	s_addc_u32 s39, s39, 0
	s_add_i32 s40, s76, s43
	global_load_lds_dwordx4 v[148:149], off
	v_lshl_add_u64 v[148:149], s[38:39], 0, v[132:133]
	s_mov_b32 m0, s40
	s_nop 0
	global_load_lds_dwordx4 v[148:149], off
	v_lshl_add_u64 v[148:149], s[38:39], 0, v[128:129]
	s_add_i32 m0, s40, 0x2000
	s_nop 0
	global_load_lds_dwordx4 v[148:149], off
	v_lshl_add_u64 v[148:149], v[218:219], 0, s[12:13]
	s_mov_b32 m0, s64
	s_nop 0
	global_load_lds_dwordx4 v[148:149], off
	v_lshl_add_u64 v[148:149], v[220:221], 0, s[12:13]
	s_mov_b32 m0, s65
	s_nop 0
	global_load_lds_dwordx4 v[148:149], off
	s_waitcnt vmcnt(8)
	s_waitcnt lgkmcnt(0)
	s_barrier
	s_setprio 1
	s_waitcnt lgkmcnt(0)
	v_mfma_f32_16x16x32_bf16 v[60:63], v[144:147], v[184:187], v[60:63]
	v_mfma_f32_16x16x32_bf16 v[56:59], v[160:163], v[184:187], v[56:59]
	v_mfma_f32_16x16x32_bf16 v[48:51], v[144:147], v[192:195], v[48:51]
	v_mfma_f32_16x16x32_bf16 v[40:43], v[160:163], v[192:195], v[40:43]
	v_mfma_f32_16x16x32_bf16 v[32:35], v[144:147], v[200:203], v[32:35]
	v_mfma_f32_16x16x32_bf16 v[24:27], v[160:163], v[200:203], v[24:27]
	v_mfma_f32_16x16x32_bf16 v[16:19], v[144:147], v[208:211], v[16:19]
	v_mfma_f32_16x16x32_bf16 v[8:11], v[160:163], v[208:211], v[8:11]
	v_mfma_f32_16x16x32_bf16 v[60:63], v[156:159], v[188:191], v[60:63]
	v_mfma_f32_16x16x32_bf16 v[56:59], v[164:167], v[188:191], v[56:59]
	v_mfma_f32_16x16x32_bf16 v[48:51], v[156:159], v[196:199], v[48:51]
	v_mfma_f32_16x16x32_bf16 v[40:43], v[164:167], v[196:199], v[40:43]
	v_mfma_f32_16x16x32_bf16 v[32:35], v[156:159], v[204:207], v[32:35]
	v_mfma_f32_16x16x32_bf16 v[24:27], v[164:167], v[204:207], v[24:27]
	v_mfma_f32_16x16x32_bf16 v[16:19], v[156:159], v[212:215], v[16:19]
	v_mfma_f32_16x16x32_bf16 v[8:11], v[164:167], v[212:215], v[8:11]
	s_setprio 0
	s_setprio 1
	v_mfma_f32_16x16x32_bf16 v[52:55], v[168:171], v[184:187], v[52:55]
	v_mfma_f32_16x16x32_bf16 v[44:47], v[176:179], v[184:187], v[44:47]
	v_mfma_f32_16x16x32_bf16 v[36:39], v[168:171], v[192:195], v[36:39]
	v_mfma_f32_16x16x32_bf16 v[28:31], v[176:179], v[192:195], v[28:31]
	v_mfma_f32_16x16x32_bf16 v[20:23], v[168:171], v[200:203], v[20:23]
	v_mfma_f32_16x16x32_bf16 v[12:15], v[176:179], v[200:203], v[12:15]
	v_mfma_f32_16x16x32_bf16 v[4:7], v[168:171], v[208:211], v[4:7]
	v_mfma_f32_16x16x32_bf16 v[0:3], v[176:179], v[208:211], v[0:3]
	v_mfma_f32_16x16x32_bf16 v[52:55], v[172:175], v[188:191], v[52:55]
	v_mfma_f32_16x16x32_bf16 v[44:47], v[180:183], v[188:191], v[44:47]
	v_mfma_f32_16x16x32_bf16 v[36:39], v[172:175], v[196:199], v[36:39]
	v_mfma_f32_16x16x32_bf16 v[28:31], v[180:183], v[196:199], v[28:31]
	v_mfma_f32_16x16x32_bf16 v[20:23], v[172:175], v[204:207], v[20:23]
	v_mfma_f32_16x16x32_bf16 v[12:15], v[180:183], v[204:207], v[12:15]
	v_mfma_f32_16x16x32_bf16 v[4:7], v[172:175], v[212:215], v[4:7]
	v_mfma_f32_16x16x32_bf16 v[0:3], v[180:183], v[212:215], v[0:3]
	s_setprio 0
	s_barrier
	s_mov_b32 s99, 0
	s_add_i32 s74, s74, 2
	s_add_u32 s36, s36, 0x100
	s_addc_u32 s37, s37, 0
	s_add_u32 s72, s72, 0x100
	s_addc_u32 s73, s73, 0
	s_cmp_gt_u32 s74, 5
	s_cbranch_scc0 .LBB0_1284
	v_lshl_add_u32 v148, s34, 8, v150
	v_lshl_or_b32 v146, s69, 8, v152
	v_lshlrev_b32_e32 v144, 11, v148
	v_lshl_add_u32 v144, v146, 1, v144
	v_mov_b32_e32 v145, v144
	global_load_dwordx4 v[156:159], v145, s[10:11]
	global_load_dwordx4 v[160:163], v145, s[10:11] offset:256
	v_add_u32_e32 v145, 0x8000, v144
	global_load_dwordx4 v[164:167], v145, s[10:11]
	global_load_dwordx4 v[168:171], v145, s[10:11] offset:256
	v_add_u32_e32 v145, 0x10000, v144
	global_load_dwordx4 v[172:175], v145, s[10:11]
	global_load_dwordx4 v[176:179], v145, s[10:11] offset:256
	v_add_u32_e32 v145, 0x18000, v144
	global_load_dwordx4 v[180:183], v145, s[10:11]
	global_load_dwordx4 v[184:187], v145, s[10:11] offset:256
	v_add_u32_e32 v145, 0x40000, v144
	global_load_dwordx4 v[188:191], v145, s[10:11]
	global_load_dwordx4 v[192:195], v145, s[10:11] offset:256
	v_add_u32_e32 v145, 0x48000, v144
	global_load_dwordx4 v[196:199], v145, s[10:11]
	global_load_dwordx4 v[200:203], v145, s[10:11] offset:256
	v_add_u32_e32 v145, 0x50000, v144
	global_load_dwordx4 v[204:207], v145, s[10:11]
	global_load_dwordx4 v[208:211], v145, s[10:11] offset:256
	v_add_u32_e32 v145, 0x58000, v144
	global_load_dwordx4 v[212:215], v145, s[10:11]
	global_load_dwordx4 v[216:219], v145, s[10:11] offset:256
	s_and_b64 vcc, exec, s[14:15]
	s_cbranch_vccz .LBB0_1287
	s_barrier
; __device__ __forceinline__ u32x4 pack8(const f32x4 a, const f32x4 b) { u32x4 w; w.x = cvt_pk_bf16(a[0], a[1]); w.y = cvt_pk_bf16(a[2], a[3]); w.z = cvt_pk_bf16(b[0], b[1]); w.w = cvt_pk_bf16(b[2], b[3]); return w; }
; __device__ __forceinline__ void unpack8(const u32x4 w, f32x4& a, f32x4& b) { a = (f32x4){bflo(w.x), bfhi(w.x), bflo(w.y), bfhi(w.y)}; b = (f32x4){bflo(w.z), bfhi(w.z), bflo(w.w), bfhi(w.w)}; }
;     __device__ __forceinline__ void operator()(const f32x4 (&acc)[2][2][4][2], const Unit& u, int wr, int wc, int fr, int fq) const {
;         const int rbase = u.pm * 256 + wr * 64 + fr, cb = u.pn * 256 + wc * 32 + fq * 8;
; #pragma unroll
;         for (int ai = 0; ai < 2; ++ai)
; #pragma unroll
;             for (int m = 0; m < 4; ++m) { const size_t ro = (size_t)(rbase + ai * 128 + m * 16) * 1024 + cb;
; #pragma unroll
;                 for (int bj = 0; bj < 2; ++bj) { f32x4 g0, g1; unpack8(*(const u32x4*)(G + ro + bj * 128), g0, g1);
;                     f32x4 v0 = acc[ai][bj][m][0] * g0, v1 = acc[ai][bj][m][1] * g1;
;                     if (!FIRST) { f32x4 o0, o1; unpack8(*(const u32x4*)(O + ro + bj * 128), o0, o1); v0 += o0; v1 += o1; }
;                     *(u32x4*)(O + ro + bj * 128) = pack8(v0, v1); }
;                 asm volatile("" ::: "memory"); }
.LBB0_1287:
	s_waitcnt vmcnt(14)
	v_mov_b32_e32 v145, v144
	v_lshlrev_b32_e32 v230, 16, v156
	v_and_b32_e32 v231, 0xffff0000, v156
	v_lshlrev_b32_e32 v232, 16, v157
	v_and_b32_e32 v233, 0xffff0000, v157
	v_lshlrev_b32_e32 v234, 16, v158
	v_and_b32_e32 v235, 0xffff0000, v158
	v_lshlrev_b32_e32 v236, 16, v159
	v_and_b32_e32 v237, 0xffff0000, v159
	v_pk_mul_f32 v[124:125], v[124:125], v[230:231]
	v_pk_mul_f32 v[126:127], v[126:127], v[232:233]
	v_pk_mul_f32 v[120:121], v[120:121], v[234:235]
	v_pk_mul_f32 v[122:123], v[122:123], v[236:237]
	v_cvt_pk_bf16_f32 v156, v124, v125
	v_cvt_pk_bf16_f32 v157, v126, v127
	v_cvt_pk_bf16_f32 v158, v120, v121
	v_cvt_pk_bf16_f32 v159, v122, v123
	global_store_dwordx4 v145, v[156:159], s[8:9]
	v_lshlrev_b32_e32 v238, 16, v160
	v_and_b32_e32 v239, 0xffff0000, v160
	v_lshlrev_b32_e32 v240, 16, v161
	v_and_b32_e32 v241, 0xffff0000, v161
	v_lshlrev_b32_e32 v242, 16, v162
	v_and_b32_e32 v243, 0xffff0000, v162
	v_lshlrev_b32_e32 v244, 16, v163
	v_and_b32_e32 v245, 0xffff0000, v163
	v_pk_mul_f32 v[116:117], v[116:117], v[238:239]
	v_pk_mul_f32 v[118:119], v[118:119], v[240:241]
	v_pk_mul_f32 v[108:109], v[108:109], v[242:243]
	v_pk_mul_f32 v[110:111], v[110:111], v[244:245]
	v_cvt_pk_bf16_f32 v160, v116, v117
	v_cvt_pk_bf16_f32 v161, v118, v119
	v_cvt_pk_bf16_f32 v162, v108, v109
	v_cvt_pk_bf16_f32 v163, v110, v111
	global_store_dwordx4 v145, v[160:163], s[8:9] offset:256
	s_waitcnt vmcnt(14)
	v_add_u32_e32 v145, 0x8000, v144
	v_lshlrev_b32_e32 v230, 16, v164
	v_and_b32_e32 v231, 0xffff0000, v164
	v_lshlrev_b32_e32 v232, 16, v165
	v_and_b32_e32 v233, 0xffff0000, v165
	v_lshlrev_b32_e32 v234, 16, v166
	v_and_b32_e32 v235, 0xffff0000, v166
	v_lshlrev_b32_e32 v236, 16, v167
	v_and_b32_e32 v237, 0xffff0000, v167
	v_pk_mul_f32 v[112:113], v[112:113], v[230:231]
	v_pk_mul_f32 v[114:115], v[114:115], v[232:233]
	v_pk_mul_f32 v[104:105], v[104:105], v[234:235]
	v_pk_mul_f32 v[106:107], v[106:107], v[236:237]
	v_cvt_pk_bf16_f32 v164, v112, v113
	v_cvt_pk_bf16_f32 v165, v114, v115
	v_cvt_pk_bf16_f32 v166, v104, v105
	v_cvt_pk_bf16_f32 v167, v106, v107
	global_store_dwordx4 v145, v[164:167], s[8:9]
	v_lshlrev_b32_e32 v238, 16, v168
	v_and_b32_e32 v239, 0xffff0000, v168
	v_lshlrev_b32_e32 v240, 16, v169
	v_and_b32_e32 v241, 0xffff0000, v169
	v_lshlrev_b32_e32 v242, 16, v170
	v_and_b32_e32 v243, 0xffff0000, v170
	v_lshlrev_b32_e32 v244, 16, v171
	v_and_b32_e32 v245, 0xffff0000, v171
	v_pk_mul_f32 v[100:101], v[100:101], v[238:239]
	v_pk_mul_f32 v[102:103], v[102:103], v[240:241]
	v_pk_mul_f32 v[92:93], v[92:93], v[242:243]
	v_pk_mul_f32 v[94:95], v[94:95], v[244:245]
	v_cvt_pk_bf16_f32 v168, v100, v101
	v_cvt_pk_bf16_f32 v169, v102, v103
	v_cvt_pk_bf16_f32 v170, v92, v93
	v_cvt_pk_bf16_f32 v171, v94, v95
	global_store_dwordx4 v145, v[168:171], s[8:9] offset:256
	s_waitcnt vmcnt(14)
	v_add_u32_e32 v145, 0x10000, v144
	v_lshlrev_b32_e32 v230, 16, v172
	v_and_b32_e32 v231, 0xffff0000, v172
	v_lshlrev_b32_e32 v232, 16, v173
	v_and_b32_e32 v233, 0xffff0000, v173
	v_lshlrev_b32_e32 v234, 16, v174
	v_and_b32_e32 v235, 0xffff0000, v174
	v_lshlrev_b32_e32 v236, 16, v175
	v_and_b32_e32 v237, 0xffff0000, v175
	v_pk_mul_f32 v[96:97], v[96:97], v[230:231]
	v_pk_mul_f32 v[98:99], v[98:99], v[232:233]
	v_pk_mul_f32 v[88:89], v[88:89], v[234:235]
	v_pk_mul_f32 v[90:91], v[90:91], v[236:237]
	v_cvt_pk_bf16_f32 v172, v96, v97
	v_cvt_pk_bf16_f32 v173, v98, v99
	v_cvt_pk_bf16_f32 v174, v88, v89
	v_cvt_pk_bf16_f32 v175, v90, v91
	global_store_dwordx4 v145, v[172:175], s[8:9]
	v_lshlrev_b32_e32 v238, 16, v176
	v_and_b32_e32 v239, 0xffff0000, v176
	v_lshlrev_b32_e32 v240, 16, v177
	v_and_b32_e32 v241, 0xffff0000, v177
	v_lshlrev_b32_e32 v242, 16, v178
	v_and_b32_e32 v243, 0xffff0000, v178
	v_lshlrev_b32_e32 v244, 16, v179
	v_and_b32_e32 v245, 0xffff0000, v179
	v_pk_mul_f32 v[84:85], v[84:85], v[238:239]
	v_pk_mul_f32 v[86:87], v[86:87], v[240:241]
	v_pk_mul_f32 v[76:77], v[76:77], v[242:243]
	v_pk_mul_f32 v[78:79], v[78:79], v[244:245]
	v_cvt_pk_bf16_f32 v176, v84, v85
	v_cvt_pk_bf16_f32 v177, v86, v87
	v_cvt_pk_bf16_f32 v178, v76, v77
	v_cvt_pk_bf16_f32 v179, v78, v79
	global_store_dwordx4 v145, v[176:179], s[8:9] offset:256
	s_waitcnt vmcnt(14)
	v_add_u32_e32 v145, 0x18000, v144
	v_lshlrev_b32_e32 v230, 16, v180
	v_and_b32_e32 v231, 0xffff0000, v180
	v_lshlrev_b32_e32 v232, 16, v181
	v_and_b32_e32 v233, 0xffff0000, v181
	v_lshlrev_b32_e32 v234, 16, v182
	v_and_b32_e32 v235, 0xffff0000, v182
	v_lshlrev_b32_e32 v236, 16, v183
	v_and_b32_e32 v237, 0xffff0000, v183
	v_pk_mul_f32 v[80:81], v[80:81], v[230:231]
	v_pk_mul_f32 v[82:83], v[82:83], v[232:233]
	v_pk_mul_f32 v[72:73], v[72:73], v[234:235]
	v_pk_mul_f32 v[74:75], v[74:75], v[236:237]
	v_cvt_pk_bf16_f32 v180, v80, v81
	v_cvt_pk_bf16_f32 v181, v82, v83
	v_cvt_pk_bf16_f32 v182, v72, v73
	v_cvt_pk_bf16_f32 v183, v74, v75
	global_store_dwordx4 v145, v[180:183], s[8:9]
	v_lshlrev_b32_e32 v238, 16, v184
	v_and_b32_e32 v239, 0xffff0000, v184
	v_lshlrev_b32_e32 v240, 16, v185
	v_and_b32_e32 v241, 0xffff0000, v185
	v_lshlrev_b32_e32 v242, 16, v186
	v_and_b32_e32 v243, 0xffff0000, v186
	v_lshlrev_b32_e32 v244, 16, v187
	v_and_b32_e32 v245, 0xffff0000, v187
	v_pk_mul_f32 v[68:69], v[68:69], v[238:239]
	v_pk_mul_f32 v[70:71], v[70:71], v[240:241]
	v_pk_mul_f32 v[64:65], v[64:65], v[242:243]
	v_pk_mul_f32 v[66:67], v[66:67], v[244:245]
	v_cvt_pk_bf16_f32 v184, v68, v69
	v_cvt_pk_bf16_f32 v185, v70, v71
	v_cvt_pk_bf16_f32 v186, v64, v65
	v_cvt_pk_bf16_f32 v187, v66, v67
	global_store_dwordx4 v145, v[184:187], s[8:9] offset:256
	s_waitcnt vmcnt(14)
; __device__ __forceinline__ u32x4 pack8(const f32x4 a, const f32x4 b) { u32x4 w; w.x = cvt_pk_bf16(a[0], a[1]); w.y = cvt_pk_bf16(a[2], a[3]); w.z = cvt_pk_bf16(b[0], b[1]); w.w = cvt_pk_bf16(b[2], b[3]); return w; }
; __device__ __forceinline__ void unpack8(const u32x4 w, f32x4& a, f32x4& b) { a = (f32x4){bflo(w.x), bfhi(w.x), bflo(w.y), bfhi(w.y)}; b = (f32x4){bflo(w.z), bfhi(w.z), bflo(w.w), bfhi(w.w)}; }
;     __device__ __forceinline__ void operator()(const f32x4 (&acc)[2][2][4][2], const Unit& u, int wr, int wc, int fr, int fq) const {
;         const int rbase = u.pm * 256 + wr * 64 + fr, cb = u.pn * 256 + wc * 32 + fq * 8;
; #pragma unroll
;         for (int ai = 0; ai < 2; ++ai)
; #pragma unroll
;             for (int m = 0; m < 4; ++m) { const size_t ro = (size_t)(rbase + ai * 128 + m * 16) * 1024 + cb;
; #pragma unroll
;                 for (int bj = 0; bj < 2; ++bj) { f32x4 g0, g1; unpack8(*(const u32x4*)(G + ro + bj * 128), g0, g1);
;                     f32x4 v0 = acc[ai][bj][m][0] * g0, v1 = acc[ai][bj][m][1] * g1;
;                     if (!FIRST) { f32x4 o0, o1; unpack8(*(const u32x4*)(O + ro + bj * 128), o0, o1); v0 += o0; v1 += o1; }
;                     *(u32x4*)(O + ro + bj * 128) = pack8(v0, v1); }
;                 asm volatile("" ::: "memory"); }
	v_add_u32_e32 v145, 0x40000, v144
	v_lshlrev_b32_e32 v230, 16, v188
	v_and_b32_e32 v231, 0xffff0000, v188
	v_lshlrev_b32_e32 v232, 16, v189
	v_and_b32_e32 v233, 0xffff0000, v189
	v_lshlrev_b32_e32 v234, 16, v190
	v_and_b32_e32 v235, 0xffff0000, v190
	v_lshlrev_b32_e32 v236, 16, v191
	v_and_b32_e32 v237, 0xffff0000, v191
	v_pk_mul_f32 v[60:61], v[60:61], v[230:231]
	v_pk_mul_f32 v[62:63], v[62:63], v[232:233]
	v_pk_mul_f32 v[56:57], v[56:57], v[234:235]
	v_pk_mul_f32 v[58:59], v[58:59], v[236:237]
	v_cvt_pk_bf16_f32 v188, v60, v61
	v_cvt_pk_bf16_f32 v189, v62, v63
	v_cvt_pk_bf16_f32 v190, v56, v57
	v_cvt_pk_bf16_f32 v191, v58, v59
	global_store_dwordx4 v145, v[188:191], s[8:9]
	v_lshlrev_b32_e32 v238, 16, v192
	v_and_b32_e32 v239, 0xffff0000, v192
	v_lshlrev_b32_e32 v240, 16, v193
	v_and_b32_e32 v241, 0xffff0000, v193
	v_lshlrev_b32_e32 v242, 16, v194
	v_and_b32_e32 v243, 0xffff0000, v194
	v_lshlrev_b32_e32 v244, 16, v195
	v_and_b32_e32 v245, 0xffff0000, v195
	v_pk_mul_f32 v[52:53], v[52:53], v[238:239]
	v_pk_mul_f32 v[54:55], v[54:55], v[240:241]
	v_pk_mul_f32 v[44:45], v[44:45], v[242:243]
	v_pk_mul_f32 v[46:47], v[46:47], v[244:245]
	v_cvt_pk_bf16_f32 v192, v52, v53
	v_cvt_pk_bf16_f32 v193, v54, v55
	v_cvt_pk_bf16_f32 v194, v44, v45
	v_cvt_pk_bf16_f32 v195, v46, v47
	global_store_dwordx4 v145, v[192:195], s[8:9] offset:256
	s_waitcnt vmcnt(14)
	v_add_u32_e32 v145, 0x48000, v144
	v_lshlrev_b32_e32 v230, 16, v196
	v_and_b32_e32 v231, 0xffff0000, v196
	v_lshlrev_b32_e32 v232, 16, v197
	v_and_b32_e32 v233, 0xffff0000, v197
	v_lshlrev_b32_e32 v234, 16, v198
	v_and_b32_e32 v235, 0xffff0000, v198
	v_lshlrev_b32_e32 v236, 16, v199
	v_and_b32_e32 v237, 0xffff0000, v199
	v_pk_mul_f32 v[48:49], v[48:49], v[230:231]
	v_pk_mul_f32 v[50:51], v[50:51], v[232:233]
	v_pk_mul_f32 v[40:41], v[40:41], v[234:235]
	v_pk_mul_f32 v[42:43], v[42:43], v[236:237]
	v_cvt_pk_bf16_f32 v196, v48, v49
	v_cvt_pk_bf16_f32 v197, v50, v51
	v_cvt_pk_bf16_f32 v198, v40, v41
	v_cvt_pk_bf16_f32 v199, v42, v43
	global_store_dwordx4 v145, v[196:199], s[8:9]
	v_lshlrev_b32_e32 v238, 16, v200
	v_and_b32_e32 v239, 0xffff0000, v200
	v_lshlrev_b32_e32 v240, 16, v201
	v_and_b32_e32 v241, 0xffff0000, v201
	v_lshlrev_b32_e32 v242, 16, v202
	v_and_b32_e32 v243, 0xffff0000, v202
	v_lshlrev_b32_e32 v244, 16, v203
	v_and_b32_e32 v245, 0xffff0000, v203
	v_pk_mul_f32 v[36:37], v[36:37], v[238:239]
	v_pk_mul_f32 v[38:39], v[38:39], v[240:241]
	v_pk_mul_f32 v[28:29], v[28:29], v[242:243]
	v_pk_mul_f32 v[30:31], v[30:31], v[244:245]
	v_cvt_pk_bf16_f32 v200, v36, v37
	v_cvt_pk_bf16_f32 v201, v38, v39
	v_cvt_pk_bf16_f32 v202, v28, v29
	v_cvt_pk_bf16_f32 v203, v30, v31
	global_store_dwordx4 v145, v[200:203], s[8:9] offset:256
	s_waitcnt vmcnt(14)
	v_add_u32_e32 v145, 0x50000, v144
	v_lshlrev_b32_e32 v230, 16, v204
	v_and_b32_e32 v231, 0xffff0000, v204
	v_lshlrev_b32_e32 v232, 16, v205
	v_and_b32_e32 v233, 0xffff0000, v205
	v_lshlrev_b32_e32 v234, 16, v206
	v_and_b32_e32 v235, 0xffff0000, v206
	v_lshlrev_b32_e32 v236, 16, v207
	v_and_b32_e32 v237, 0xffff0000, v207
	v_pk_mul_f32 v[32:33], v[32:33], v[230:231]
	v_pk_mul_f32 v[34:35], v[34:35], v[232:233]
	v_pk_mul_f32 v[24:25], v[24:25], v[234:235]
	v_pk_mul_f32 v[26:27], v[26:27], v[236:237]
	v_cvt_pk_bf16_f32 v204, v32, v33
	v_cvt_pk_bf16_f32 v205, v34, v35
	v_cvt_pk_bf16_f32 v206, v24, v25
	v_cvt_pk_bf16_f32 v207, v26, v27
	global_store_dwordx4 v145, v[204:207], s[8:9]
	v_lshlrev_b32_e32 v238, 16, v208
	v_and_b32_e32 v239, 0xffff0000, v208
	v_lshlrev_b32_e32 v240, 16, v209
	v_and_b32_e32 v241, 0xffff0000, v209
	v_lshlrev_b32_e32 v242, 16, v210
	v_and_b32_e32 v243, 0xffff0000, v210
	v_lshlrev_b32_e32 v244, 16, v211
	v_and_b32_e32 v245, 0xffff0000, v211
	v_pk_mul_f32 v[20:21], v[20:21], v[238:239]
	v_pk_mul_f32 v[22:23], v[22:23], v[240:241]
	v_pk_mul_f32 v[12:13], v[12:13], v[242:243]
	v_pk_mul_f32 v[14:15], v[14:15], v[244:245]
	v_cvt_pk_bf16_f32 v208, v20, v21
	v_cvt_pk_bf16_f32 v209, v22, v23
	v_cvt_pk_bf16_f32 v210, v12, v13
	v_cvt_pk_bf16_f32 v211, v14, v15
	global_store_dwordx4 v145, v[208:211], s[8:9] offset:256
	s_waitcnt vmcnt(14)
	v_add_u32_e32 v145, 0x58000, v144
	v_lshlrev_b32_e32 v230, 16, v212
	v_and_b32_e32 v231, 0xffff0000, v212
	v_lshlrev_b32_e32 v232, 16, v213
	v_and_b32_e32 v233, 0xffff0000, v213
	v_lshlrev_b32_e32 v234, 16, v214
	v_and_b32_e32 v235, 0xffff0000, v214
	v_lshlrev_b32_e32 v236, 16, v215
	v_and_b32_e32 v237, 0xffff0000, v215
	v_pk_mul_f32 v[16:17], v[16:17], v[230:231]
	v_pk_mul_f32 v[18:19], v[18:19], v[232:233]
	v_pk_mul_f32 v[8:9], v[8:9], v[234:235]
	v_pk_mul_f32 v[10:11], v[10:11], v[236:237]
	v_cvt_pk_bf16_f32 v212, v16, v17
	v_cvt_pk_bf16_f32 v213, v18, v19
	v_cvt_pk_bf16_f32 v214, v8, v9
	v_cvt_pk_bf16_f32 v215, v10, v11
	global_store_dwordx4 v145, v[212:215], s[8:9]
	v_lshlrev_b32_e32 v238, 16, v216
	v_and_b32_e32 v239, 0xffff0000, v216
	v_lshlrev_b32_e32 v240, 16, v217
	v_and_b32_e32 v241, 0xffff0000, v217
	v_lshlrev_b32_e32 v242, 16, v218
	v_and_b32_e32 v243, 0xffff0000, v218
	v_lshlrev_b32_e32 v244, 16, v219
	v_and_b32_e32 v245, 0xffff0000, v219
	v_pk_mul_f32 v[4:5], v[4:5], v[238:239]
	v_pk_mul_f32 v[6:7], v[6:7], v[240:241]
	v_pk_mul_f32 v[0:1], v[0:1], v[242:243]
	v_pk_mul_f32 v[2:3], v[2:3], v[244:245]
	v_cvt_pk_bf16_f32 v216, v4, v5
	v_cvt_pk_bf16_f32 v217, v6, v7
	v_cvt_pk_bf16_f32 v218, v0, v1
	v_cvt_pk_bf16_f32 v219, v2, v3
	global_store_dwordx4 v145, v[216:219], s[8:9] offset:256
	s_andn2_b64 vcc, exec, s[0:1]
	s_mov_b64 s[0:1], -1
	s_cbranch_vccnz .LBB0_1280
	s_andn2_b64 vcc, exec, s[6:7]
	s_cbranch_vccnz .LBB0_1279
	s_barrier
	s_branch .LBB0_1279
